# MLA: one barrier per tile per wave (leading waves after softmax, trailing after QK/PV), persistent row-sum accumulators, max exchange only on rare path, lean staging
# speedup vs baseline: 1.0411x; 1.0270x over previous
; #define SLOAD(j) do { const size_t krow = (size_t)(seq0 + key0 + 64 * (j) + sr); kst = *(const bf16x8*)(Kp + krow * ldk + sc); vstg = *(const bf16x8*)(Vp + krow * ldk + sc); \
;         if (MODE == 2) { if (tid < 256) pst = *(const bf16x8*)(Kpe + (size_t)(seq0 + key0 + 64 * (j) + pr) * 32 + pc); } } while (0)
; #define SWRITE(b) do { *(bf16x8*)(lds + A_K0 + (b) * A_KBUF + sr * KSTR + sc * 2) = kst; *(bf16x8*)(lds + A_V0 + (b) * A_VBUF + vst) = vstg; \
;         if (MODE == 2) { if (tid < 256) *(bf16x8*)(lds + A_K0 + (b) * A_KBUF + pr * KSTR + 128 + pc * 2) = pst; } } while (0)
; #define SLOAD(S, j) do { const size_t krow = (size_t)(seq0 + 64 * (j) + sr); ks##S = *(const bf16x8*)(Kp + krow * 1024 + sc); vs##S = *(const bf16x8*)(Vp + krow * 1024 + sc); \
;         ps##S = *(const bf16x8*)(Kpe + (size_t)(seq0 + 64 * (j) + pr) * 32 + pc); } while (0)
; #define SWRITE(b, S) do { *(bf16x8*)(lds + A_K0 + (b) * A_KBUF + sr * KSTR + sc * 2) = ks##S; *(bf16x8*)(lds + A_V0 + (b) * A_VBUF + vst) = vs##S; \
;         if (tid < 256) *(bf16x8*)(lds + A_K0 + (b) * A_KBUF + pr * KSTR + 128 + pc * 2) = ps##S; } while (0)
; #define SBAR() __builtin_amdgcn_sched_barrier(0)
; #define SLOAD(S, t) do { const int t_ = (t); if (t_ + 1 < NT) { ks##S = *(const bf16x8*)(Kth + (size_t)(t_ + 1) * 65536); ps##S = *(const bf16x8*)(Pth + (size_t)(t_ + 1) * 2048); } \
;         if (t_ < NT) { vs##S = *(const bf16x8*)(Vth + (size_t)t_ * 65536); } } while (0)
; #define SWRITE(S, t, kw, vw) do { const int t_ = (t); if (t_ + 1 < NT) { *(bf16x8*)((kw) + sr * KSTR + sc * 2) = ks##S; if (tid < 256) *(bf16x8*)((kw) + pr * KSTR + 128 + pc * 2) = ps##S; } \
;         if (t_ < NT) *(bf16x8*)((vw) + vst) = vs##S; } while (0)
; #define SBAR() __builtin_amdgcn_sched_barrier(0)
; __device__ __forceinline__ void mla_unit2(const Params& P, unsigned char* lds, int h, int rb, int grp, bool dry = false) {
;     ...
;     { const bf16x8 k0v = *(const bf16x8*)(Kp + (size_t)(seq0 + sr) * 1024 + sc); const bf16x8 p0v = *(const bf16x8*)(Kpe + (size_t)(seq0 + pr) * 32 + pc);
;       SLOAD(E, hoff); if (hoff) SLOAD(O, 0);
;       *(bf16x8*)(lds + A_K0 + sr * KSTR + sc * 2) = k0v; if (tid < 256) *(bf16x8*)(lds + A_K0 + pr * KSTR + 128 + pc * 2) = p0v; }
;     HBAR();
;     if (hoff) { SWRITE(O, 0, kwO, vwO); HBAR(); }
;     for (int i = 0; i < NT; i += 2) {
;         SLOAD(O, i + 1 + hoff); SBAR();
.LBB0_933:
	s_or_b64 exec, exec, s[44:45]
	s_waitcnt vmcnt(0)
	v_and_b32_e32 v0, 0x1fffff0, v11
	v_lshlrev_b32_e32 v1, 1, v11
	v_and_or_b32 v0, v1, 8, v0
	s_and_b64 s[4:5], exec, s[16:17]
	v_lshrrev_b32_e32 v0, 2, v0
	v_lshrrev_b32_e32 v2, 5, v12
	s_cselect_b32 s4, 0, 0x3400
	v_lshrrev_b32_e32 v1, 1, v11
	v_or_b32_e32 v0, v0, v2
	v_and_b32_e32 v2, 3, v11
	s_add_i32 s41, s4, 0
	v_and_or_b32 v1, v1, 4, v2
	v_and_b32_e32 v2, 48, v144
	s_and_b64 s[4:5], exec, s[16:17]
	s_waitcnt lgkmcnt(0)
	s_barrier
	v_lshl_or_b32 v1, v1, 6, v2
	s_cselect_b32 s4, 0x2000, 0
	v_lshl_or_b32 v161, v0, 9, v1
	s_add_i32 s59, s4, 0
	s_andn2_b64 vcc, exec, s[10:11]
	s_cbranch_vccnz .LBB0_937
	v_add3_u32 v0, s41, v48, v144
	ds_write_b128 v0, v[136:139]
	s_and_saveexec_b64 s[10:11], s[8:9]
	v_add3_u32 v0, s41, v49, v156
	ds_write_b128 v0, v[140:143] offset:128
	s_or_b64 exec, exec, s[10:11]
	v_add_u32_e32 v0, s59, v161
	ds_write_b128 v0, v[132:135] offset:26624
	s_waitcnt lgkmcnt(0)
.LBB0_937:
	s_add_i32 s44, s40, 2
	s_cmp_lt_i32 s44, s54
	s_cselect_b64 s[46:47], -1, 0
	s_cmp_ge_i32 s44, s54
	s_cbranch_scc1 .LBB0_939
	s_ashr_i32 s45, s44, 31
	s_lshl_b64 s[4:5], s[44:45], 17
	v_lshl_add_u64 v[0:1], v[32:33], 0, s[4:5]
	s_lshl_b64 s[4:5], s[44:45], 12
	v_lshl_add_u64 v[2:3], v[34:35], 0, s[4:5]
	global_load_dwordx4 v[136:139], v[0:1], off
	global_load_dwordx4 v[140:143], v[2:3], off

; #define SWRITE(b) do { *(bf16x8*)(lds + A_K0 + (b) * A_KBUF + sr * KSTR + sc * 2) = kst; *(bf16x8*)(lds + A_V0 + (b) * A_VBUF + vst) = vstg; \
;         if (MODE == 2) { if (tid < 256) *(bf16x8*)(lds + A_K0 + (b) * A_KBUF + pr * KSTR + 128 + pc * 2) = pst; } } while (0)
; #define SWRITE(b, S) do { *(bf16x8*)(lds + A_K0 + (b) * A_KBUF + sr * KSTR + sc * 2) = ks##S; *(bf16x8*)(lds + A_V0 + (b) * A_VBUF + vst) = vs##S; \
;         if (tid < 256) *(bf16x8*)(lds + A_K0 + (b) * A_KBUF + pr * KSTR + 128 + pc * 2) = ps##S; } while (0)
; #define SBAR() __builtin_amdgcn_sched_barrier(0)
; #define SWRITE(S, t, kw, vw) do { const int t_ = (t); if (t_ + 1 < NT) { *(bf16x8*)((kw) + sr * KSTR + sc * 2) = ks##S; if (tid < 256) *(bf16x8*)((kw) + pr * KSTR + 128 + pc * 2) = ps##S; } \
;         if (t_ < NT) *(bf16x8*)((vw) + vst) = vs##S; } while (0)
; #define HBAR() do { asm volatile("s_waitcnt lgkmcnt(0)" ::: "memory"); __builtin_amdgcn_s_barrier(); asm volatile("" ::: "memory"); } while (0)
; #define SBAR() __builtin_amdgcn_sched_barrier(0)
; __device__ __forceinline__ void mla_unit2(const Params& P, unsigned char* lds, int h, int rb, int grp, bool dry = false) {
;     ...
;         mla_qkt_neg(p0, p1, negm, K0, qr, r32, hi);
;         if (i > 0) { pv_both_kp(o[0], o[1], vb0 + A_VBUF, pa0, pa1, pa2, pa3); }
;         HBAR();
;         __builtin_amdgcn_s_setprio(1);
;         SWRITE(E, i + hoff, kwE, vwE); SBAR();
.LBB0_941:
	s_and_b64 s[4:5], exec, s[16:17]
	s_cselect_b32 s4, 0x3400, 0
	s_add_i32 s4, s4, 0
	v_mov_b32_e32 v1, s4
	v_mad_u32_u24 v0, v195, s93, 0
	v_mad_u32_u24 v155, v10, s93, v1
	v_add_u32_e32 v46, s4, v48
	v_add_u32_e32 v157, v0, v154
	ds_read_b128 v[0:3], v157
	ds_read_b128 v[38:41], v157 offset:32
	ds_read_b128 v[16:19], v157 offset:6656
	ds_read_b128 v[42:45], v157 offset:6688
	s_waitcnt lgkmcnt(3)
	v_mfma_f32_32x32x16_bf16 v[0:15], v[0:3], v[96:99], 0
	s_waitcnt lgkmcnt(1)
	v_mfma_f32_32x32x16_bf16 v[16:31], v[16:19], v[96:99], 0
	v_mfma_f32_32x32x16_bf16 v[0:15], v[38:41], v[100:103], v[0:15]
	s_waitcnt lgkmcnt(0)
	v_mfma_f32_32x32x16_bf16 v[16:31], v[42:45], v[100:103], v[16:31]
	ds_read_b128 v[38:41], v157 offset:64
	ds_read_b128 v[42:45], v157 offset:96
	s_waitcnt lgkmcnt(1)
	v_mfma_f32_32x32x16_bf16 v[0:15], v[38:41], v[104:107], v[0:15]
	ds_read_b128 v[38:41], v157 offset:6720
	ds_read_b128 v[50:53], v157 offset:6752
	s_waitcnt lgkmcnt(1)
	v_mfma_f32_32x32x16_bf16 v[16:31], v[38:41], v[104:107], v[16:31]
	v_mfma_f32_32x32x16_bf16 v[0:15], v[42:45], v[108:111], v[0:15]
	ds_read_b128 v[38:41], v157 offset:128
	ds_read_b128 v[42:45], v157 offset:160
	s_waitcnt lgkmcnt(2)
	v_mfma_f32_32x32x16_bf16 v[16:31], v[50:53], v[108:111], v[16:31]
	s_waitcnt lgkmcnt(1)
	v_mfma_f32_32x32x16_bf16 v[0:15], v[38:41], v[112:115], v[0:15]
	ds_read_b128 v[38:41], v157 offset:6784
	ds_read_b128 v[50:53], v157 offset:6816
	s_waitcnt lgkmcnt(0)
	s_cmp_lg_u32 s40, 0
	s_cbranch_scc0 .Lmla_nobar1
	s_barrier
.Lmla_nobar1:
	s_waitcnt lgkmcnt(1)
	v_mfma_f32_32x32x16_bf16 v[16:31], v[38:41], v[112:115], v[16:31]
	v_mfma_f32_32x32x16_bf16 v[0:15], v[42:45], v[116:119], v[0:15]
	s_waitcnt lgkmcnt(0)
	v_mfma_f32_32x32x16_bf16 v[16:31], v[50:53], v[116:119], v[16:31]
	s_setprio 1
	s_cmp_ge_i32 s40, s55
	v_add_u32_e32 v196, v46, v144
	s_cbranch_scc1 .LBB0_945
	ds_write_b128 v196, v[120:123]
	s_and_saveexec_b64 s[48:49], s[8:9]
	v_add_u32_e32 v38, v155, v156
	ds_write_b128 v38, v[124:127] offset:128
	s_or_b64 exec, exec, s[48:49]

; #define SLOAD(j) do { const size_t krow = (size_t)(seq0 + key0 + 64 * (j) + sr); kst = *(const bf16x8*)(Kp + krow * ldk + sc); vstg = *(const bf16x8*)(Vp + krow * ldk + sc); \
;         if (MODE == 2) { if (tid < 256) pst = *(const bf16x8*)(Kpe + (size_t)(seq0 + key0 + 64 * (j) + pr) * 32 + pc); } } while (0)
; #define SLOAD(S, j) do { const size_t krow = (size_t)(seq0 + 64 * (j) + sr); ks##S = *(const bf16x8*)(Kp + krow * 1024 + sc); vs##S = *(const bf16x8*)(Vp + krow * 1024 + sc); \
;         ps##S = *(const bf16x8*)(Kpe + (size_t)(seq0 + 64 * (j) + pr) * 32 + pc); } while (0)
; __device__ __forceinline__ void mla_softmax_rel_kp(f32x16& p0, f32x16& p1, f32x16& negm, bool first, float& l_reg, float& alpha, bf16x8& pa0, bf16x8& pa1, bf16x8& pa2, bf16x8& pa3) {
;     float pmax = p0[0];
; #pragma unroll
;     for (int r = 1; r < 16; ++r) pmax = fmaxf(pmax, p0[r]);
; #pragma unroll
;     for (int r = 0; r < 16; ++r) pmax = fmaxf(pmax, p1[r]);
;     { auto rr = __builtin_amdgcn_permlane32_swap(__float_as_uint(pmax), __float_as_uint(pmax), false, false); pmax = fmaxf(__uint_as_float(rr[0]), __uint_as_float(rr[1])); }
;     alpha = 1.f;
;     if (__builtin_expect(first || !__all(pmax <= THR2), 0)) {
;         const float d = first ? pmax : fmaxf(pmax, 0.f);
;         if (!first) alpha = __builtin_amdgcn_exp2f(-d);
;         const float nm = negm[0] - d;
; #pragma unroll
;         for (int r = 0; r < 16; ++r) { negm[r] = nm; p0[r] -= d; p1[r] -= d; }
;     }
; #pragma unroll
;     for (int r = 0; r < 16; ++r) { p0[r] = __builtin_amdgcn_exp2f(p0[r]); p1[r] = __builtin_amdgcn_exp2f(p1[r]); }
;     float ps = 0.f;
; #pragma unroll
;     for (int r = 0; r < 16; ++r) ps += p0[r];
; #pragma unroll
;     for (int r = 0; r < 16; ++r) ps += p1[r];
;     { auto rr = __builtin_amdgcn_permlane32_swap(__float_as_uint(ps), __float_as_uint(ps), false, false); ps = __uint_as_float(rr[0]) + __uint_as_float(rr[1]); }
;     l_reg = l_reg * alpha + ps;
;     pa0 = pack8(p0, 0); pa1 = pack8(p0, 8); pa2 = pack8(p1, 0); pa3 = pack8(p1, 8);
; __device__ __forceinline__ void mla_unit2(const Params& P, unsigned char* lds, int h, int rb, int grp, bool dry = false) {
;     ...
;         mla_softmax_rel_kp(p0, p1, negm, first, l_reg, alpha, pa0, pa1, pa2, pa3); first = false; RESC(alpha);
;         __builtin_amdgcn_s_setprio(0);
;         HBAR();
;         SLOAD(E, i + 2 + hoff); SBAR();
.LBB0_947:
	v_max_f32_e32 v38, v1, v1
	v_max_f32_e32 v39, v0, v0
	v_max_f32_e32 v38, v39, v38
	v_max3_f32 v38, v38, v2, v3
	v_max3_f32 v38, v38, v4, v5
	v_max3_f32 v38, v38, v6, v7
	v_max3_f32 v38, v38, v8, v9
	v_max3_f32 v38, v38, v10, v11
	v_max3_f32 v38, v38, v12, v13
	v_max3_f32 v38, v38, v14, v15
	v_max3_f32 v38, v38, v16, v17
	v_max3_f32 v38, v38, v18, v19
	v_max3_f32 v38, v38, v20, v21
	v_max3_f32 v38, v38, v22, v23
	v_max3_f32 v38, v38, v24, v25
	v_max3_f32 v38, v38, v26, v27
	v_max3_f32 v38, v38, v28, v29
	v_max3_f32 v38, v38, v30, v31
	v_mov_b32_e32 v39, v38
	s_nop 1
	v_permlane32_swap_b32_e32 v38, v39
	v_max_f32_e32 v39, v39, v39
	v_max_f32_e32 v38, v38, v38
	v_max_f32_e32 v38, v38, v39
	v_sub_f32_e32 v0, v0, v38
	v_sub_f32_e32 v1, v1, v38
	v_exp_f32_e32 v0, v0
	v_sub_f32_e32 v2, v2, v38
	v_exp_f32_e32 v1, v1
	v_sub_f32_e32 v3, v3, v38
	v_exp_f32_e32 v2, v2
	v_sub_f32_e32 v16, v16, v38
	v_sub_f32_e32 v4, v4, v38
	v_exp_f32_e32 v3, v3
	v_sub_f32_e32 v5, v5, v38
	v_exp_f32_e32 v39, v16
	v_exp_f32_e32 v4, v4
	v_add_f32_e32 v16, 0, v0
	v_sub_f32_e32 v6, v6, v38
	v_exp_f32_e32 v5, v5
	v_add_f32_e32 v16, v1, v16
	v_sub_f32_e32 v7, v7, v38
	v_exp_f32_e32 v6, v6
	v_add_f32_e32 v16, v2, v16
	v_sub_f32_e32 v8, v8, v38
	v_exp_f32_e32 v7, v7
	v_add_f32_e32 v16, v3, v16
	v_sub_f32_e32 v9, v9, v38
	v_exp_f32_e32 v8, v8
	v_add_f32_e32 v16, v4, v16
	v_sub_f32_e32 v10, v10, v38
	v_exp_f32_e32 v9, v9
	v_add_f32_e32 v16, v5, v16
	v_sub_f32_e32 v11, v11, v38
	v_exp_f32_e32 v10, v10
	v_add_f32_e32 v16, v6, v16
	v_sub_f32_e32 v12, v12, v38
	v_exp_f32_e32 v11, v11
	v_add_f32_e32 v16, v7, v16
	v_sub_f32_e32 v13, v13, v38
	v_exp_f32_e32 v12, v12
	v_add_f32_e32 v16, v8, v16
	v_sub_f32_e32 v14, v14, v38
	v_exp_f32_e32 v13, v13
	v_add_f32_e32 v16, v9, v16
	v_sub_f32_e32 v15, v15, v38
	v_exp_f32_e32 v14, v14
	v_add_f32_e32 v16, v10, v16
	v_exp_f32_e32 v15, v15
	v_add_f32_e32 v16, v11, v16
	v_sub_f32_e32 v17, v17, v38
	v_add_f32_e32 v16, v12, v16
	v_sub_f32_e32 v18, v18, v38
	v_exp_f32_e32 v40, v17
	v_add_f32_e32 v16, v13, v16
	v_sub_f32_e32 v19, v19, v38
	v_exp_f32_e32 v41, v18
	v_add_f32_e32 v16, v14, v16
	v_sub_f32_e32 v20, v20, v38
	v_exp_f32_e32 v42, v19
	v_add_f32_e32 v16, v15, v16
	v_sub_f32_e32 v21, v21, v38
	v_exp_f32_e32 v20, v20
	v_add_f32_e32 v16, v39, v16
	v_sub_f32_e32 v22, v22, v38
	v_exp_f32_e32 v21, v21
	v_add_f32_e32 v16, v40, v16
	v_sub_f32_e32 v23, v23, v38
	v_exp_f32_e32 v22, v22
	v_add_f32_e32 v16, v41, v16
	v_sub_f32_e32 v24, v24, v38
	v_exp_f32_e32 v23, v23
	v_add_f32_e32 v16, v42, v16
	v_sub_f32_e32 v25, v25, v38
	v_exp_f32_e32 v24, v24
	v_add_f32_e32 v16, v20, v16
	v_sub_f32_e32 v26, v26, v38
	v_exp_f32_e32 v25, v25
	v_add_f32_e32 v16, v21, v16
	v_sub_f32_e32 v27, v27, v38
	v_exp_f32_e32 v26, v26
	v_add_f32_e32 v16, v22, v16
	v_sub_f32_e32 v28, v28, v38
	v_exp_f32_e32 v27, v27
	v_add_f32_e32 v16, v23, v16
	v_sub_f32_e32 v29, v29, v38
	v_exp_f32_e32 v28, v28
	v_add_f32_e32 v16, v24, v16
	v_sub_f32_e32 v30, v30, v38
	v_exp_f32_e32 v29, v29
	v_add_f32_e32 v16, v25, v16
	v_sub_f32_e32 v31, v31, v38
	v_exp_f32_e32 v30, v30
	v_add_f32_e32 v16, v26, v16
	v_exp_f32_e32 v31, v31
	v_add_f32_e32 v16, v27, v16
	v_add_f32_e32 v16, v28, v16
	v_add_f32_e32 v16, v29, v16
	v_add_f32_e32 v16, v30, v16
	v_add_f32_e32 v93, v31, v16
	v_mov_b32_e32 v158, v93
	s_nop 1
	v_permlane32_swap_b32_e32 v93, v158
	v_cvt_pk_bf16_f32 v16, v0, v1
	v_cvt_pk_bf16_f32 v17, v2, v3
	v_cvt_pk_bf16_f32 v18, v4, v5
	v_cvt_pk_bf16_f32 v19, v6, v7
	v_cvt_pk_bf16_f32 v88, v8, v9
	v_cvt_pk_bf16_f32 v89, v10, v11
	v_cvt_pk_bf16_f32 v90, v12, v13
	v_cvt_pk_bf16_f32 v91, v14, v15
	v_cvt_pk_bf16_f32 v84, v39, v40
	v_cvt_pk_bf16_f32 v85, v41, v42
	v_cvt_pk_bf16_f32 v86, v20, v21
	v_cvt_pk_bf16_f32 v87, v22, v23
	v_cvt_pk_bf16_f32 v80, v24, v25
	v_cvt_pk_bf16_f32 v81, v26, v27
	v_cvt_pk_bf16_f32 v82, v28, v29
	v_cvt_pk_bf16_f32 v83, v30, v31
	s_setprio 0
	s_waitcnt lgkmcnt(0)
	s_cmp_eq_u32 s40, 0
	s_cbranch_scc0 .Lmla_nobar2
	s_barrier
.Lmla_nobar2:
	s_add_i32 s12, s40, 3
	s_cmp_ge_i32 s12, s54
	s_cbranch_scc1 .LBB0_949
	s_ashr_i32 s13, s12, 31
	s_lshl_b64 s[4:5], s[12:13], 17
	v_lshl_add_u64 v[0:1], v[32:33], 0, s[4:5]
	s_lshl_b64 s[4:5], s[12:13], 12
	v_lshl_add_u64 v[2:3], v[34:35], 0, s[4:5]
	global_load_dwordx4 v[120:123], v[0:1], off
	global_load_dwordx4 v[124:127], v[2:3], off

; #define SWRITE(b) do { *(bf16x8*)(lds + A_K0 + (b) * A_KBUF + sr * KSTR + sc * 2) = kst; *(bf16x8*)(lds + A_V0 + (b) * A_VBUF + vst) = vstg; \
;         if (MODE == 2) { if (tid < 256) *(bf16x8*)(lds + A_K0 + (b) * A_KBUF + pr * KSTR + 128 + pc * 2) = pst; } } while (0)
; #define SWRITE(b, S) do { *(bf16x8*)(lds + A_K0 + (b) * A_KBUF + sr * KSTR + sc * 2) = ks##S; *(bf16x8*)(lds + A_V0 + (b) * A_VBUF + vst) = vs##S; \
;         if (tid < 256) *(bf16x8*)(lds + A_K0 + (b) * A_KBUF + pr * KSTR + 128 + pc * 2) = ps##S; } while (0)
; #define SBAR() __builtin_amdgcn_sched_barrier(0)
; __device__ __forceinline__ int v_rd_base_kp(int lane) { return ((lane & 3) << 3) | (((lane >> 2) & 3) << 6) | (((lane >> 4) & 1) << 5) | (((lane >> 5) & 1) << 10); }
; #define SWRITE(S, t, kw, vw) do { const int t_ = (t); if (t_ + 1 < NT) { *(bf16x8*)((kw) + sr * KSTR + sc * 2) = ks##S; if (tid < 256) *(bf16x8*)((kw) + pr * KSTR + 128 + pc * 2) = ps##S; } \
;         if (t_ < NT) *(bf16x8*)((vw) + vst) = vs##S; } while (0)
; #define HBAR() do { asm volatile("s_waitcnt lgkmcnt(0)" ::: "memory"); __builtin_amdgcn_s_barrier(); asm volatile("" ::: "memory"); } while (0)
; #define SBAR() __builtin_amdgcn_sched_barrier(0)
; __device__ __forceinline__ void mla_unit2(const Params& P, unsigned char* lds, int h, int rb, int grp, bool dry = false) {
;     ...
;     const int vb0 = (int)(uintptr_t)(lds + A_V0) + v_rd_base_kp(lane);
;     const unsigned char* K0 = lds + A_K0; const unsigned char* K1 = lds + A_K0 + A_KBUF;
;     ...
;         mla_qkt_neg(p0, p1, negm, K1, qr, r32, hi);
;         pv_both_kp(o[0], o[1], vb0, pa0, pa1, pa2, pa3);
;         HBAR();
;         __builtin_amdgcn_s_setprio(1);
;         SWRITE(O, i + 1 + hoff, kwO, vwO); SBAR();
.LBB0_951:
	v_and_b32_e32 v162, 63, v160
	v_lshlrev_b32_e32 v1, 4, v162
	v_lshlrev_b32_e32 v0, 3, v162
	v_and_b32_e32 v1, 0xc0, v1
	v_and_or_b32 v0, v0, 24, v1
	v_lshlrev_b32_e32 v1, 1, v162
	v_lshlrev_b32_e32 v2, 5, v162
	v_add_u32_e32 v150, s41, v48
	v_add_u32_e32 v198, s41, v49
	s_add_i32 s41, 0, 0x6800
	v_and_b32_e32 v1, 32, v1
	v_and_b32_e32 v2, 0x400, v2
	s_cmp_lg_u32 s41, -1
	v_or3_b32 v159, v0, v1, v2
	s_cselect_b32 s4, s41, 0
	v_sub_f32_e32 v32, 0, v38
	v_add_u32_e32 v199, s4, v159
	v_mov_b32_e32 v33, v32
	v_mov_b32_e32 v34, v32
	v_mov_b32_e32 v35, v32
	v_mov_b32_e32 v36, v32
	v_mov_b32_e32 v37, v32
	v_mov_b32_e32 v38, v32
	v_mov_b32_e32 v39, v32
	v_mov_b32_e32 v40, v32
	v_mov_b32_e32 v41, v32
	v_mov_b32_e32 v42, v32
	v_mov_b32_e32 v43, v32
	v_mov_b32_e32 v44, v32
	v_mov_b32_e32 v45, v32
	v_mov_b32_e32 v46, v32
	v_mov_b32_e32 v47, v32
	ds_read_b128 v[0:3], v157 offset:13312
	ds_read_b128 v[4:7], v157 offset:13344
	v_mov_b64_e32 v[78:79], v[46:47]
	v_mov_b64_e32 v[76:77], v[44:45]
	v_mov_b64_e32 v[74:75], v[42:43]
	s_waitcnt lgkmcnt(1)
	v_mfma_f32_32x32x16_bf16 v[48:63], v[0:3], v[96:99], v[32:47]
	ds_read_b128 v[0:3], v157 offset:19968
	ds_read_b128 v[8:11], v157 offset:20000
	v_mov_b64_e32 v[72:73], v[40:41]
	v_mov_b64_e32 v[70:71], v[38:39]
	v_mov_b64_e32 v[68:69], v[36:37]
	v_mov_b64_e32 v[66:67], v[34:35]
	v_mov_b64_e32 v[64:65], v[32:33]
	s_waitcnt lgkmcnt(2)
	v_mfma_f32_32x32x16_bf16 v[48:63], v[4:7], v[100:103], v[48:63]
	s_waitcnt lgkmcnt(1)
	v_mfma_f32_32x32x16_bf16 v[64:79], v[0:3], v[96:99], v[64:79]
	ds_read_b128 v[0:3], v157 offset:13376
	ds_read_b128 v[4:7], v157 offset:13408
	s_waitcnt lgkmcnt(2)
	v_mfma_f32_32x32x16_bf16 v[64:79], v[8:11], v[100:103], v[64:79]
	s_waitcnt lgkmcnt(1)
	v_mfma_f32_32x32x16_bf16 v[48:63], v[0:3], v[104:107], v[48:63]
	ds_read_b128 v[0:3], v157 offset:20032
	ds_read_b128 v[8:11], v157 offset:20064
	s_waitcnt lgkmcnt(1)
	v_mfma_f32_32x32x16_bf16 v[64:79], v[0:3], v[104:107], v[64:79]
	v_mfma_f32_32x32x16_bf16 v[48:63], v[4:7], v[108:111], v[48:63]
	ds_read_b128 v[0:3], v157 offset:13440
	ds_read_b128 v[4:7], v157 offset:13472
	s_waitcnt lgkmcnt(2)
	v_mfma_f32_32x32x16_bf16 v[64:79], v[8:11], v[108:111], v[64:79]
	s_waitcnt lgkmcnt(1)
	v_mfma_f32_32x32x16_bf16 v[48:63], v[0:3], v[112:115], v[48:63]
	ds_read_b128 v[0:3], v157 offset:20096
	ds_read_b128 v[8:11], v157 offset:20128
	ds_read_b64_tr_b16 v[12:13], v199 offset:0
	ds_read_b64_tr_b16 v[14:15], v199 offset:0x100
	ds_read_b64_tr_b16 v[20:21], v199 offset:0x800
	ds_read_b64_tr_b16 v[22:23], v199 offset:0x900
	ds_read_b64_tr_b16 v[24:25], v199 offset:0x1000
	ds_read_b64_tr_b16 v[26:27], v199 offset:0x1100
	s_waitcnt lgkmcnt(1)
	v_mfma_f32_32x32x16_bf16 v[64:79], v[0:3], v[112:115], v[64:79]
	ds_read_b64_tr_b16 v[28:29], v199 offset:0x1800
	ds_read_b64_tr_b16 v[30:31], v199 offset:0x1900
	ds_read_b64_tr_b16 v[34:35], v199 offset:0x200
	ds_read_b64_tr_b16 v[36:37], v199 offset:0x300
	ds_read_b64_tr_b16 v[38:39], v199 offset:0xa00
	ds_read_b64_tr_b16 v[40:41], v199 offset:0xb00
	ds_read_b64_tr_b16 v[42:43], v199 offset:0x1200
	v_mfma_f32_32x32x16_bf16 v[48:63], v[4:7], v[116:119], v[48:63]
	ds_read_b64_tr_b16 v[44:45], v199 offset:0x1300
	ds_read_b64_tr_b16 v[146:147], v199 offset:0x1a00
	ds_read_b64_tr_b16 v[148:149], v199 offset:0x1b00
	s_waitcnt lgkmcnt(8)
	s_waitcnt lgkmcnt(0)
	v_mfma_f32_32x32x16_bf16 v[64:79], v[8:11], v[116:119], v[64:79]
	v_mfma_f32_32x32x16_bf16 v[0:15], v[16:19], v[12:15], 0
	s_waitcnt lgkmcnt(0)
	v_mfma_f32_32x32x16_bf16 v[0:15], v[88:91], v[20:23], v[0:15]
	v_mfma_f32_32x32x16_bf16 v[0:15], v[84:87], v[24:27], v[0:15]
	v_mfma_f32_32x32x16_bf16 v[0:15], v[80:83], v[28:31], v[0:15]
	v_mfma_f32_32x32x16_bf16 v[16:31], v[16:19], v[34:37], 0
	s_waitcnt lgkmcnt(0)
	s_cmp_lg_u32 s40, 0
	s_cbranch_scc0 .Lmla_nobar3
	s_barrier
.Lmla_nobar3:
	v_mfma_f32_32x32x16_bf16 v[16:31], v[88:91], v[38:41], v[16:31]
	v_mfma_f32_32x32x16_bf16 v[16:31], v[84:87], v[42:45], v[16:31]
	v_mfma_f32_32x32x16_bf16 v[16:31], v[80:83], v[146:149], v[16:31]
	s_setprio 1
	s_and_b64 vcc, exec, s[12:13]
	v_add_u32_e32 v200, v150, v144
	s_cbranch_vccnz .LBB0_955
	s_waitcnt vmcnt(1)
	ds_write_b128 v200, v[136:139]
	s_and_saveexec_b64 s[12:13], s[8:9]
	s_cbranch_execz .LBB0_954
	v_add_u32_e32 v33, v198, v156
	s_waitcnt vmcnt(0)
	ds_write_b128 v33, v[140:143] offset:128

; #define SLOAD(j) do { const size_t krow = (size_t)(seq0 + key0 + 64 * (j) + sr); kst = *(const bf16x8*)(Kp + krow * ldk + sc); vstg = *(const bf16x8*)(Vp + krow * ldk + sc); \
;         if (MODE == 2) { if (tid < 256) pst = *(const bf16x8*)(Kpe + (size_t)(seq0 + key0 + 64 * (j) + pr) * 32 + pc); } } while (0)
; #define SWRITE(b) do { *(bf16x8*)(lds + A_K0 + (b) * A_KBUF + sr * KSTR + sc * 2) = kst; *(bf16x8*)(lds + A_V0 + (b) * A_VBUF + vst) = vstg; \
;         if (MODE == 2) { if (tid < 256) *(bf16x8*)(lds + A_K0 + (b) * A_KBUF + pr * KSTR + 128 + pc * 2) = pst; } } while (0)
; #define SLOAD(S, j) do { const size_t krow = (size_t)(seq0 + 64 * (j) + sr); ks##S = *(const bf16x8*)(Kp + krow * 1024 + sc); vs##S = *(const bf16x8*)(Vp + krow * 1024 + sc); \
;         ps##S = *(const bf16x8*)(Kpe + (size_t)(seq0 + 64 * (j) + pr) * 32 + pc); } while (0)
; #define SWRITE(b, S) do { *(bf16x8*)(lds + A_K0 + (b) * A_KBUF + sr * KSTR + sc * 2) = ks##S; *(bf16x8*)(lds + A_V0 + (b) * A_VBUF + vst) = vs##S; \
;         if (tid < 256) *(bf16x8*)(lds + A_K0 + (b) * A_KBUF + pr * KSTR + 128 + pc * 2) = ps##S; } while (0)
; #define SBAR() __builtin_amdgcn_sched_barrier(0)
; #define HBAR() do { asm volatile("s_waitcnt lgkmcnt(0)" ::: "memory"); __builtin_amdgcn_s_barrier(); asm volatile("" ::: "memory"); } while (0)
; __device__ __forceinline__ void mla_unit2(const Params& P, unsigned char* lds, int h, int rb, int grp, bool dry = false) {
;     ...
;     for (int i = 0; i < NT; i += 2) {
;         SLOAD(O, i + 1 + hoff); SBAR();
;         mla_qkt_neg(p0, p1, negm, K0, qr, r32, hi);
;         if (i > 0) { pv_both_kp(o[0], o[1], vb0 + A_VBUF, pa0, pa1, pa2, pa3); }
;         HBAR();
;         __builtin_amdgcn_s_setprio(1);
;         SWRITE(E, i + hoff, kwE, vwE); SBAR();
;         mla_softmax_rel_kp(p0, p1, negm, first, l_reg, alpha, pa0, pa1, pa2, pa3); first = false; RESC(alpha);
;         __builtin_amdgcn_s_setprio(0);
;         HBAR();
;         SLOAD(E, i + 2 + hoff); SBAR();
;         mla_qkt_neg(p0, p1, negm, K1, qr, r32, hi);
;         pv_both_kp(o[0], o[1], vb0, pa0, pa1, pa2, pa3);
;         HBAR();
;         __builtin_amdgcn_s_setprio(1);
;         SWRITE(O, i + 1 + hoff, kwO, vwO); SBAR();
;         mla_softmax_rel_kp(p0, p1, negm, first, l_reg, alpha, pa0, pa1, pa2, pa3); first = false; RESC(alpha);
;         __builtin_amdgcn_s_setprio(0);
;         HBAR();
;     }
.LBB0_962:
	s_cmp_lg_u32 s41, -1
	v_add_f32_e32 v36, v93, v158
	s_cselect_b32 s4, s41, 0
	v_add_f32_e32 v36, 0, v36
	v_add_f32_e32 v203, v34, v35
	s_addk_i32 s4, 0x2000
	v_fmac_f32_e32 v203, v36, v33
	v_add_u32_e32 v204, s4, v159
	s_setprio 0
	s_waitcnt lgkmcnt(0)
	s_cmp_eq_u32 s40, 0
	s_cbranch_scc0 .Lmla_nobar0
	s_barrier
.Lmla_nobar0:
	s_ashr_i32 s41, s40, 31
	s_lshl_b64 s[4:5], s[40:41], 17
	v_lshl_add_u64 v[34:35], s[4:5], 0, v[94:95]
	s_lshl_b64 s[4:5], s[40:41], 12
	v_and_b32_e32 v33, 7, v160
	s_add_u32 s4, s52, s4
	v_lshl_or_b32 v34, v33, 4, v34
	s_addc_u32 s5, 0, s5
	v_mov_b32_e32 v93, v145
	v_and_b32_e32 v33, 3, v160
	v_lshl_add_u64 v[158:159], s[42:43], 1, v[34:35]
	v_lshl_add_u64 v[34:35], s[4:5], 0, v[92:93]
	v_lshlrev_b32_e32 v144, 4, v33
	v_lshl_add_u64 v[160:161], v[34:35], 0, v[144:145]
	s_mov_b32 s41, 2
	s_nop 0
	v_readfirstlane_b32 s60, v158
	v_readfirstlane_b32 s61, v159
	v_readfirstlane_b32 s64, v160
	v_readfirstlane_b32 s65, v161
	v_subrev_u32_e32 v166, s60, v158
	v_subrev_u32_e32 v167, s64, v160
	s_add_u32 s60, s60, s36
	s_addc_u32 s61, s61, s37
	s_add_u32 s64, s64, s36
	s_addc_u32 s65, s65, s37
	s_add_u32 s62, s60, 0x18060000
	s_addc_u32 s63, s61, 0
	s_add_u32 s60, s60, 0x14080000
	s_addc_u32 s61, s61, 0
	s_add_u32 s64, s64, 0x304000
	s_addc_u32 s65, s65, 0
	v_mov_b32_e32 v33, v32
	v_mov_b32_e32 v34, v32
	v_mov_b32_e32 v35, v32
	v_mov_b32_e32 v36, v32
	v_mov_b32_e32 v37, v32
	v_mov_b32_e32 v38, v32
	v_mov_b32_e32 v39, v32
	v_mov_b32_e32 v40, v32
	v_mov_b32_e32 v41, v32
	v_mov_b32_e32 v42, v32
	v_mov_b32_e32 v43, v32
	v_mov_b32_e32 v44, v32
	v_mov_b32_e32 v45, v32
	v_mov_b32_e32 v46, v32
	v_mov_b32_e32 v47, v32
	v_mul_f32_e32 v236, 0.5, v203
	v_mov_b32_e32 v237, 0
	v_mov_b32_e32 v144, 1.0
	v_mov_b32_e32 v235, 1.0
	v_add_u32_e32 v238, v155, v156
	v_add_u32_e32 v239, v198, v156
	s_branch .LBB0_965
.LBB0_963:
	s_or_b64 exec, exec, s[12:13]
	s_waitcnt lgkmcnt(0)
	v_add_u32_e32 v78, s46, v154
	ds_read_b128 v[66:69], v78 offset:43232
	ds_read_b128 v[70:73], v78 offset:43200
	ds_read_b128 v[74:77], v78 offset:43168
	ds_read_b128 v[82:85], v78 offset:43136
	s_waitcnt lgkmcnt(0)
	s_waitcnt lgkmcnt(3)
	v_pk_mul_f32 v[12:13], v[12:13], v[66:67]
	s_waitcnt lgkmcnt(2)
	v_pk_mul_f32 v[8:9], v[8:9], v[70:71]
	s_waitcnt lgkmcnt(1)
	v_pk_mul_f32 v[4:5], v[4:5], v[74:75]
	v_pk_mul_f32 v[14:15], v[14:15], v[68:69]
	v_pk_mul_f32 v[10:11], v[10:11], v[72:73]
	v_pk_mul_f32 v[6:7], v[6:7], v[76:77]
	s_waitcnt lgkmcnt(0)
	v_pk_mul_f32 v[2:3], v[2:3], v[84:85]
	v_pk_mul_f32 v[0:1], v[0:1], v[82:83]
	v_pk_mul_f32 v[28:29], v[28:29], v[66:67]
	v_pk_mul_f32 v[24:25], v[24:25], v[70:71]
	v_pk_mul_f32 v[20:21], v[20:21], v[74:75]
	v_pk_mul_f32 v[30:31], v[30:31], v[68:69]
	v_pk_mul_f32 v[26:27], v[26:27], v[72:73]
	v_pk_mul_f32 v[22:23], v[22:23], v[76:77]
	v_pk_mul_f32 v[18:19], v[18:19], v[84:85]
	v_pk_mul_f32 v[16:17], v[16:17], v[82:83]
	v_mov_b32_e32 v235, 1.0
.LBB0_964:
	s_add_i32 s41, s41, 2
	s_waitcnt lgkmcnt(0)
	s_cmp_eq_u32 s40, 0
	s_cbranch_scc0 .Lmla_nobar7
	s_barrier
.Lmla_nobar7:
	s_add_u32 s60, s60, 0x20000
	s_addc_u32 s61, s61, 0
	s_add_u32 s62, s62, 0x20000
	s_addc_u32 s63, s63, 0
	s_add_u32 s64, s64, 0x1000
	s_addc_u32 s65, s65, 0
	s_cmp_lt_u32 s41, s54
	s_cbranch_scc0 .LBB0_997

; #define SLOAD(j) do { const size_t krow = (size_t)(seq0 + key0 + 64 * (j) + sr); kst = *(const bf16x8*)(Kp + krow * ldk + sc); vstg = *(const bf16x8*)(Vp + krow * ldk + sc); \
;         if (MODE == 2) { if (tid < 256) pst = *(const bf16x8*)(Kpe + (size_t)(seq0 + key0 + 64 * (j) + pr) * 32 + pc); } } while (0)
; #define SWRITE(b) do { *(bf16x8*)(lds + A_K0 + (b) * A_KBUF + sr * KSTR + sc * 2) = kst; *(bf16x8*)(lds + A_V0 + (b) * A_VBUF + vst) = vstg; \
;         if (MODE == 2) { if (tid < 256) *(bf16x8*)(lds + A_K0 + (b) * A_KBUF + pr * KSTR + 128 + pc * 2) = pst; } } while (0)
; #define SLOAD(S, j) do { const size_t krow = (size_t)(seq0 + 64 * (j) + sr); ks##S = *(const bf16x8*)(Kp + krow * 1024 + sc); vs##S = *(const bf16x8*)(Vp + krow * 1024 + sc); \
;         ps##S = *(const bf16x8*)(Kpe + (size_t)(seq0 + 64 * (j) + pr) * 32 + pc); } while (0)
; #define SWRITE(b, S) do { *(bf16x8*)(lds + A_K0 + (b) * A_KBUF + sr * KSTR + sc * 2) = ks##S; *(bf16x8*)(lds + A_V0 + (b) * A_VBUF + vst) = vs##S; \
;         if (tid < 256) *(bf16x8*)(lds + A_K0 + (b) * A_KBUF + pr * KSTR + 128 + pc * 2) = ps##S; } while (0)
; #define SBAR() __builtin_amdgcn_sched_barrier(0)
; #define HBAR() do { asm volatile("s_waitcnt lgkmcnt(0)" ::: "memory"); __builtin_amdgcn_s_barrier(); asm volatile("" ::: "memory"); } while (0)
; __device__ __forceinline__ void mla_softmax_rel_kp(f32x16& p0, f32x16& p1, f32x16& negm, bool first, float& l_reg, float& alpha, bf16x8& pa0, bf16x8& pa1, bf16x8& pa2, bf16x8& pa3) {
;     float pmax = p0[0];
; #pragma unroll
;     for (int r = 1; r < 16; ++r) pmax = fmaxf(pmax, p0[r]);
; #pragma unroll
;     for (int r = 0; r < 16; ++r) pmax = fmaxf(pmax, p1[r]);
;     { auto rr = __builtin_amdgcn_permlane32_swap(__float_as_uint(pmax), __float_as_uint(pmax), false, false); pmax = fmaxf(__uint_as_float(rr[0]), __uint_as_float(rr[1])); }
;     alpha = 1.f;
;     if (__builtin_expect(first || !__all(pmax <= THR2), 0)) {
; __device__ __forceinline__ void mla_unit2(const Params& P, unsigned char* lds, int h, int rb, int grp, bool dry = false) {
;     ...
;         SLOAD(O, i + 1 + hoff); SBAR();
;         mla_qkt_neg(p0, p1, negm, K0, qr, r32, hi);
;         if (i > 0) { pv_both_kp(o[0], o[1], vb0 + A_VBUF, pa0, pa1, pa2, pa3); }
;         HBAR();
;         __builtin_amdgcn_s_setprio(1);
;         SWRITE(E, i + hoff, kwE, vwE); SBAR();
.LBB0_969:
	ds_read_b128 v[80:83], v157
	ds_read_b128 v[146:149], v157 offset:32
	ds_read_b128 v[150:153], v157 offset:6656
	ds_read_b128 v[168:171], v157 offset:6688
	s_waitcnt lgkmcnt(3)
	v_mfma_f32_32x32x16_bf16 v[64:79], v[80:83], v[96:99], v[32:47]
	s_waitcnt lgkmcnt(1)
	v_mfma_f32_32x32x16_bf16 v[80:95], v[150:153], v[96:99], v[32:47]
	v_mfma_f32_32x32x16_bf16 v[64:79], v[146:149], v[100:103], v[64:79]
	ds_read_b128 v[146:149], v157 offset:64
	ds_read_b128 v[150:153], v157 offset:96
	s_waitcnt lgkmcnt(2)
	v_mfma_f32_32x32x16_bf16 v[80:95], v[168:171], v[100:103], v[80:95]
	s_waitcnt lgkmcnt(1)
	v_mfma_f32_32x32x16_bf16 v[64:79], v[146:149], v[104:107], v[64:79]
	ds_read_b128 v[146:149], v157 offset:6720
	ds_read_b128 v[168:171], v157 offset:6752
	s_waitcnt lgkmcnt(1)
	v_mfma_f32_32x32x16_bf16 v[80:95], v[146:149], v[104:107], v[80:95]
	v_mfma_f32_32x32x16_bf16 v[64:79], v[150:153], v[108:111], v[64:79]
	ds_read_b128 v[146:149], v157 offset:128
	ds_read_b128 v[150:153], v157 offset:160
	s_waitcnt lgkmcnt(2)
	v_mfma_f32_32x32x16_bf16 v[80:95], v[168:171], v[108:111], v[80:95]
	s_waitcnt lgkmcnt(1)
	v_mfma_f32_32x32x16_bf16 v[64:79], v[146:149], v[112:115], v[64:79]
	ds_read_b128 v[146:149], v157 offset:6784
	ds_read_b128 v[168:171], v157 offset:6816
	ds_read_b64_tr_b16 v[182:183], v204 offset:0
	ds_read_b64_tr_b16 v[184:185], v204 offset:0x100
	s_waitcnt lgkmcnt(1)
	v_mfma_f32_32x32x16_bf16 v[80:95], v[146:149], v[112:115], v[80:95]
	ds_read_b64_tr_b16 v[146:147], v204 offset:0x800
	ds_read_b64_tr_b16 v[148:149], v204 offset:0x900
	ds_read_b64_tr_b16 v[186:187], v204 offset:0x1000
	ds_read_b64_tr_b16 v[188:189], v204 offset:0x1100
	ds_read_b64_tr_b16 v[190:191], v204 offset:0x1800
	ds_read_b64_tr_b16 v[192:193], v204 offset:0x1900
	ds_read_b64_tr_b16 v[206:207], v204 offset:0x200
	ds_read_b64_tr_b16 v[208:209], v204 offset:0x300
	v_mfma_f32_32x32x16_bf16 v[64:79], v[150:153], v[116:119], v[64:79]
	ds_read_b64_tr_b16 v[150:151], v204 offset:0xa00
	ds_read_b64_tr_b16 v[152:153], v204 offset:0xb00
	ds_read_b64_tr_b16 v[210:211], v204 offset:0x1200
	ds_read_b64_tr_b16 v[212:213], v204 offset:0x1300
	ds_read_b64_tr_b16 v[214:215], v204 offset:0x1a00
	ds_read_b64_tr_b16 v[216:217], v204 offset:0x1b00
	s_waitcnt lgkmcnt(8)
	s_waitcnt lgkmcnt(0)
	v_mfma_f32_32x32x16_bf16 v[80:95], v[168:171], v[116:119], v[80:95]
	v_mfma_f32_32x32x16_bf16 v[0:15], v[60:63], v[182:185], v[0:15]
	s_waitcnt lgkmcnt(0)
	v_mfma_f32_32x32x16_bf16 v[0:15], v[56:59], v[146:149], v[0:15]
	v_mfma_f32_32x32x16_bf16 v[0:15], v[52:55], v[186:189], v[0:15]
	v_mfma_f32_32x32x16_bf16 v[0:15], v[48:51], v[190:193], v[0:15]
	v_mfma_f32_32x32x16_bf16 v[16:31], v[60:63], v[206:209], v[16:31]
	s_waitcnt lgkmcnt(0)
	s_cmp_lg_u32 s40, 0
	s_cbranch_scc0 .Lmla_nobar4
	s_barrier
.Lmla_nobar4:
	v_mfma_f32_32x32x16_bf16 v[16:31], v[56:59], v[150:153], v[16:31]
	v_mfma_f32_32x32x16_bf16 v[16:31], v[52:55], v[210:213], v[16:31]
	v_mfma_f32_32x32x16_bf16 v[16:31], v[48:51], v[214:217], v[16:31]
	s_cmp_lg_u64 s[44:45], 0
	s_cbranch_scc0 .Lmla_w1_tail
	s_waitcnt vmcnt(3)
	ds_write_b128 v196, v[120:123]
	ds_write_b128 v197, v[128:131] offset:26624
	s_cmp_lg_u32 s8, 0
	s_cbranch_scc0 .LBB0_975
	ds_write_b128 v238, v[124:127] offset:128
.LBB0_975:
	v_max3_f32 v48, v64, v65, v66
	v_max3_f32 v49, v67, v68, v69
	v_max3_f32 v50, v70, v71, v72
	v_max3_f32 v48, v48, v73, v74
	v_max3_f32 v49, v49, v75, v76
	v_max3_f32 v50, v50, v77, v78
	v_max3_f32 v48, v48, v79, v80
	v_max3_f32 v49, v49, v81, v82
	v_max3_f32 v50, v50, v83, v84
	v_max3_f32 v48, v48, v85, v86
	v_max3_f32 v49, v49, v87, v88
	v_max3_f32 v50, v50, v89, v90
	v_max3_f32 v48, v48, v91, v92
	v_max3_f32 v49, v49, v93, v94
	v_max3_f32 v48, v48, v49, v50
	v_max_f32_e32 v48, v48, v95
	v_cmp_ge_f32_e32 vcc, s94, v48
	s_cmp_eq_u64 vcc, exec
	s_cbranch_scc0 .LBB0_995
; #define SLOAD(j) do { const size_t krow = (size_t)(seq0 + key0 + 64 * (j) + sr); kst = *(const bf16x8*)(Kp + krow * ldk + sc); vstg = *(const bf16x8*)(Vp + krow * ldk + sc); \
;         if (MODE == 2) { if (tid < 256) pst = *(const bf16x8*)(Kpe + (size_t)(seq0 + key0 + 64 * (j) + pr) * 32 + pc); } } while (0)
; #define SLOAD(S, j) do { const size_t krow = (size_t)(seq0 + 64 * (j) + sr); ks##S = *(const bf16x8*)(Kp + krow * 1024 + sc); vs##S = *(const bf16x8*)(Vp + krow * 1024 + sc); \
;         ps##S = *(const bf16x8*)(Kpe + (size_t)(seq0 + 64 * (j) + pr) * 32 + pc); } while (0)
; #define RESC(a) do { if (__any((a) < 1.f)) { if (hi == 0) al_l[r32] = (a); LDS_WAIT(); \
;         _Pragma("unroll") for (int d = 0; d < 2; ++d) _Pragma("unroll") for (int r = 0; r < 16; ++r) o[d][r] *= al_l[crow(r, hi)]; LDS_WAIT(); } } while (0)
; #define SBAR() __builtin_amdgcn_sched_barrier(0)
; #define SLOAD(S, t) do { const int t_ = (t); if (t_ + 1 < NT) { ks##S = *(const bf16x8*)(Kth + (size_t)(t_ + 1) * 65536); ps##S = *(const bf16x8*)(Pth + (size_t)(t_ + 1) * 2048); } \
;         if (t_ < NT) { vs##S = *(const bf16x8*)(Vth + (size_t)t_ * 65536); } } while (0)
; #define SBAR() __builtin_amdgcn_sched_barrier(0)
; __device__ __forceinline__ void mla_softmax_rel_kp(f32x16& p0, f32x16& p1, f32x16& negm, bool first, float& l_reg, float& alpha, bf16x8& pa0, bf16x8& pa1, bf16x8& pa2, bf16x8& pa3) {
;     ...
; #pragma unroll
;     for (int r = 0; r < 16; ++r) { p0[r] = __builtin_amdgcn_exp2f(p0[r]); p1[r] = __builtin_amdgcn_exp2f(p1[r]); }
;     float ps = 0.f;
; #pragma unroll
;     for (int r = 0; r < 16; ++r) ps += p0[r];
; #pragma unroll
;     for (int r = 0; r < 16; ++r) ps += p1[r];
;     { auto rr = __builtin_amdgcn_permlane32_swap(__float_as_uint(ps), __float_as_uint(ps), false, false); ps = __uint_as_float(rr[0]) + __uint_as_float(rr[1]); }
;     l_reg = l_reg * alpha + ps;
;     pa0 = pack8(p0, 0); pa1 = pack8(p0, 8); pa2 = pack8(p1, 0); pa3 = pack8(p1, 8);
; __device__ __forceinline__ void mla_unit2(const Params& P, unsigned char* lds, int h, int rb, int grp, bool dry = false) {
;     ...
;         mla_softmax_rel_kp(p0, p1, negm, first, l_reg, alpha, pa0, pa1, pa2, pa3); first = false; RESC(alpha);
;         __builtin_amdgcn_s_setprio(0);
;         HBAR();
;         SLOAD(E, i + 2 + hoff); SBAR();
.LBB0_977:
	v_exp_f32_e32 v64, v64
	v_exp_f32_e32 v65, v65
	v_exp_f32_e32 v66, v66
	v_add_f32_e32 v236, v64, v236
	v_exp_f32_e32 v67, v67
	v_add_f32_e32 v237, v65, v237
	v_exp_f32_e32 v68, v68
	v_add_f32_e32 v236, v66, v236
	v_exp_f32_e32 v69, v69
	v_add_f32_e32 v237, v67, v237
	v_exp_f32_e32 v70, v70
	v_add_f32_e32 v236, v68, v236
	v_exp_f32_e32 v71, v71
	v_add_f32_e32 v237, v69, v237
	v_exp_f32_e32 v72, v72
	v_add_f32_e32 v236, v70, v236
	v_exp_f32_e32 v73, v73
	v_add_f32_e32 v237, v71, v237
	v_exp_f32_e32 v74, v74
	v_add_f32_e32 v236, v72, v236
	v_exp_f32_e32 v75, v75
	v_add_f32_e32 v237, v73, v237
	v_exp_f32_e32 v76, v76
	v_add_f32_e32 v236, v74, v236
	v_exp_f32_e32 v77, v77
	v_add_f32_e32 v237, v75, v237
	v_exp_f32_e32 v78, v78
	v_add_f32_e32 v236, v76, v236
	v_exp_f32_e32 v79, v79
	v_add_f32_e32 v237, v77, v237
	v_exp_f32_e32 v80, v80
	v_add_f32_e32 v236, v78, v236
	v_exp_f32_e32 v81, v81
	v_add_f32_e32 v237, v79, v237
	v_exp_f32_e32 v82, v82
	v_add_f32_e32 v236, v80, v236
	v_exp_f32_e32 v83, v83
	v_add_f32_e32 v237, v81, v237
	v_exp_f32_e32 v84, v84
	v_add_f32_e32 v236, v82, v236
	v_exp_f32_e32 v85, v85
	v_add_f32_e32 v237, v83, v237
	v_exp_f32_e32 v86, v86
	v_add_f32_e32 v236, v84, v236
	v_exp_f32_e32 v87, v87
	v_add_f32_e32 v237, v85, v237
	v_exp_f32_e32 v88, v88
	v_add_f32_e32 v236, v86, v236
	v_exp_f32_e32 v89, v89
	v_add_f32_e32 v237, v87, v237
	v_exp_f32_e32 v90, v90
	v_add_f32_e32 v236, v88, v236
	v_exp_f32_e32 v91, v91
	v_add_f32_e32 v237, v89, v237
	v_exp_f32_e32 v92, v92
	v_add_f32_e32 v236, v90, v236
	v_exp_f32_e32 v93, v93
	v_add_f32_e32 v237, v91, v237
	v_exp_f32_e32 v94, v94
	v_add_f32_e32 v236, v92, v236
	v_exp_f32_e32 v95, v95
	v_add_f32_e32 v237, v93, v237
	v_add_f32_e32 v236, v94, v236
	v_add_f32_e32 v237, v95, v237
	v_cmp_gt_f32_e32 vcc, 1.0, v144
	v_cvt_pk_bf16_f32 v87, v86, v87
	v_cvt_pk_bf16_f32 v86, v84, v85
	v_cvt_pk_bf16_f32 v85, v82, v83
	v_cvt_pk_bf16_f32 v84, v80, v81
	v_cvt_pk_bf16_f32 v82, v92, v93
	v_cvt_pk_bf16_f32 v83, v94, v95
	v_cvt_pk_bf16_f32 v80, v88, v89
	v_cvt_pk_bf16_f32 v81, v90, v91
	v_cvt_pk_bf16_f32 v92, v64, v65
	v_cvt_pk_bf16_f32 v93, v66, v67
	v_cvt_pk_bf16_f32 v94, v68, v69
	v_cvt_pk_bf16_f32 v95, v70, v71
	v_cvt_pk_bf16_f32 v88, v72, v73
	v_cvt_pk_bf16_f32 v89, v74, v75
	v_cvt_pk_bf16_f32 v90, v76, v77
	v_cvt_pk_bf16_f32 v91, v78, v79
	s_cbranch_vccz .LBB0_981
	s_and_saveexec_b64 s[12:13], s[10:11]
	ds_write_b32 v202, v144 offset:43136
	s_or_b64 exec, exec, s[12:13]
	s_waitcnt lgkmcnt(0)
	v_add_u32_e32 v76, s46, v154
	ds_read_b128 v[64:67], v76 offset:43232
	ds_read_b128 v[68:71], v76 offset:43200
	ds_read_b128 v[72:75], v76 offset:43168
	ds_read_b128 v[76:79], v76 offset:43136
	s_waitcnt lgkmcnt(0)
	s_waitcnt lgkmcnt(3)
	v_pk_mul_f32 v[12:13], v[12:13], v[64:65]
	s_waitcnt lgkmcnt(2)
	v_pk_mul_f32 v[8:9], v[8:9], v[68:69]
	s_waitcnt lgkmcnt(1)
	v_pk_mul_f32 v[4:5], v[4:5], v[72:73]
	v_pk_mul_f32 v[14:15], v[14:15], v[66:67]
	v_pk_mul_f32 v[10:11], v[10:11], v[70:71]
	v_pk_mul_f32 v[6:7], v[6:7], v[74:75]
	s_waitcnt lgkmcnt(0)
	v_pk_mul_f32 v[2:3], v[2:3], v[78:79]
	v_pk_mul_f32 v[0:1], v[0:1], v[76:77]
	v_pk_mul_f32 v[28:29], v[28:29], v[64:65]
	v_pk_mul_f32 v[24:25], v[24:25], v[68:69]
	v_pk_mul_f32 v[20:21], v[20:21], v[72:73]
	v_pk_mul_f32 v[30:31], v[30:31], v[66:67]
	v_pk_mul_f32 v[26:27], v[26:27], v[70:71]
	v_pk_mul_f32 v[22:23], v[22:23], v[74:75]
	v_pk_mul_f32 v[18:19], v[18:19], v[78:79]
	v_pk_mul_f32 v[16:17], v[16:17], v[76:77]
	v_mov_b32_e32 v144, 1.0
.LBB0_981:
	s_waitcnt lgkmcnt(0)
	s_cmp_eq_u32 s40, 0
	s_cbranch_scc0 .Lmla_nobar5
	s_barrier
.Lmla_nobar5:
	s_add_u32 s60, s60, 0x20000
	s_addc_u32 s61, s61, 0
	s_add_u32 s62, s62, 0x20000
	s_addc_u32 s63, s63, 0
	s_add_u32 s64, s64, 0x1000
	s_addc_u32 s65, s65, 0
	s_add_i32 s47, s47, 3
	s_cmp_ge_i32 s47, s54
	s_cbranch_scc1 .LBB0_983
	global_load_dwordx4 v[120:123], v166, s[60:61]
	global_load_dwordx4 v[124:127], v167, s[64:65]

; #define SWRITE(b) do { *(bf16x8*)(lds + A_K0 + (b) * A_KBUF + sr * KSTR + sc * 2) = kst; *(bf16x8*)(lds + A_V0 + (b) * A_VBUF + vst) = vstg; \
;         if (MODE == 2) { if (tid < 256) *(bf16x8*)(lds + A_K0 + (b) * A_KBUF + pr * KSTR + 128 + pc * 2) = pst; } } while (0)
; #define SBAR() __builtin_amdgcn_sched_barrier(0)
; #define SBAR() __builtin_amdgcn_sched_barrier(0)
; __device__ __forceinline__ void mla_softmax_rel_kp(f32x16& p0, f32x16& p1, f32x16& negm, bool first, float& l_reg, float& alpha, bf16x8& pa0, bf16x8& pa1, bf16x8& pa2, bf16x8& pa3) {
;     float pmax = p0[0];
; #pragma unroll
;     for (int r = 1; r < 16; ++r) pmax = fmaxf(pmax, p0[r]);
; #pragma unroll
;     for (int r = 0; r < 16; ++r) pmax = fmaxf(pmax, p1[r]);
;     { auto rr = __builtin_amdgcn_permlane32_swap(__float_as_uint(pmax), __float_as_uint(pmax), false, false); pmax = fmaxf(__uint_as_float(rr[0]), __uint_as_float(rr[1])); }
;     alpha = 1.f;
;     if (__builtin_expect(first || !__all(pmax <= THR2), 0)) {
;         const float d = first ? pmax : fmaxf(pmax, 0.f);
;         if (!first) alpha = __builtin_amdgcn_exp2f(-d);
;         const float nm = negm[0] - d;
; #pragma unroll
;         for (int r = 0; r < 16; ++r) { negm[r] = nm; p0[r] -= d; p1[r] -= d; }
;     }
; #pragma unroll
;     for (int r = 0; r < 16; ++r) { p0[r] = __builtin_amdgcn_exp2f(p0[r]); p1[r] = __builtin_amdgcn_exp2f(p1[r]); }
;     float ps = 0.f;
; #pragma unroll
;     for (int r = 0; r < 16; ++r) ps += p0[r];
; #pragma unroll
;     for (int r = 0; r < 16; ++r) ps += p1[r];
;     { auto rr = __builtin_amdgcn_permlane32_swap(__float_as_uint(ps), __float_as_uint(ps), false, false); ps = __uint_as_float(rr[0]) + __uint_as_float(rr[1]); }
;     l_reg = l_reg * alpha + ps;
;     pa0 = pack8(p0, 0); pa1 = pack8(p0, 8); pa2 = pack8(p1, 0); pa3 = pack8(p1, 8);
; __device__ __forceinline__ void mla_unit2(const Params& P, unsigned char* lds, int h, int rb, int grp, bool dry = false) {
;     ...
;         mla_qkt_neg(p0, p1, negm, K1, qr, r32, hi);
;         pv_both_kp(o[0], o[1], vb0, pa0, pa1, pa2, pa3);
;         HBAR();
;         __builtin_amdgcn_s_setprio(1);
;         SWRITE(O, i + 1 + hoff, kwO, vwO); SBAR();
;         mla_softmax_rel_kp(p0, p1, negm, first, l_reg, alpha, pa0, pa1, pa2, pa3); first = false; RESC(alpha);
;         __builtin_amdgcn_s_setprio(0);
;         HBAR();
.LBB0_985:
	ds_read_b128 v[146:149], v157 offset:13312
	ds_read_b128 v[150:153], v157 offset:13344
	s_waitcnt lgkmcnt(1)
	v_mfma_f32_32x32x16_bf16 v[64:79], v[146:149], v[96:99], v[32:47]
	ds_read_b128 v[146:149], v157 offset:19968
	ds_read_b128 v[162:165], v157 offset:20000
	s_waitcnt lgkmcnt(1)
	v_mfma_f32_32x32x16_bf16 v[48:63], v[146:149], v[96:99], v[32:47]
	v_mfma_f32_32x32x16_bf16 v[64:79], v[150:153], v[100:103], v[64:79]
	ds_read_b128 v[146:149], v157 offset:13376
	ds_read_b128 v[150:153], v157 offset:13408
	s_waitcnt lgkmcnt(2)
	v_mfma_f32_32x32x16_bf16 v[48:63], v[162:165], v[100:103], v[48:63]
	s_waitcnt lgkmcnt(1)
	v_mfma_f32_32x32x16_bf16 v[64:79], v[146:149], v[104:107], v[64:79]
	ds_read_b128 v[146:149], v157 offset:20032
	ds_read_b128 v[162:165], v157 offset:20064
	s_waitcnt lgkmcnt(1)
	v_mfma_f32_32x32x16_bf16 v[48:63], v[146:149], v[104:107], v[48:63]
	v_mfma_f32_32x32x16_bf16 v[64:79], v[150:153], v[108:111], v[64:79]
	ds_read_b128 v[146:149], v157 offset:13440
	ds_read_b128 v[150:153], v157 offset:13472
	s_waitcnt lgkmcnt(2)
	v_mfma_f32_32x32x16_bf16 v[48:63], v[162:165], v[108:111], v[48:63]
	s_waitcnt lgkmcnt(1)
	v_mfma_f32_32x32x16_bf16 v[64:79], v[146:149], v[112:115], v[64:79]
	ds_read_b128 v[146:149], v157 offset:20096
	ds_read_b128 v[162:165], v157 offset:20128
	ds_read_b64_tr_b16 v[168:169], v199 offset:0
	ds_read_b64_tr_b16 v[170:171], v199 offset:0x100
	s_waitcnt lgkmcnt(1)
	v_mfma_f32_32x32x16_bf16 v[48:63], v[146:149], v[112:115], v[48:63]
	ds_read_b64_tr_b16 v[146:147], v199 offset:0x800
	ds_read_b64_tr_b16 v[148:149], v199 offset:0x900
	ds_read_b64_tr_b16 v[182:183], v199 offset:0x1000
	ds_read_b64_tr_b16 v[184:185], v199 offset:0x1100
	ds_read_b64_tr_b16 v[186:187], v199 offset:0x1800
	ds_read_b64_tr_b16 v[188:189], v199 offset:0x1900
	ds_read_b64_tr_b16 v[190:191], v199 offset:0x200
	ds_read_b64_tr_b16 v[192:193], v199 offset:0x300
	v_mfma_f32_32x32x16_bf16 v[64:79], v[150:153], v[116:119], v[64:79]
	ds_read_b64_tr_b16 v[150:151], v199 offset:0xa00
	ds_read_b64_tr_b16 v[152:153], v199 offset:0xb00
	ds_read_b64_tr_b16 v[208:209], v199 offset:0x1200
	ds_read_b64_tr_b16 v[210:211], v199 offset:0x1300
	ds_read_b64_tr_b16 v[212:213], v199 offset:0x1a00
	ds_read_b64_tr_b16 v[214:215], v199 offset:0x1b00
	s_waitcnt lgkmcnt(8)
	s_waitcnt lgkmcnt(0)
	v_mfma_f32_32x32x16_bf16 v[48:63], v[162:165], v[116:119], v[48:63]
	v_mfma_f32_32x32x16_bf16 v[0:15], v[92:95], v[168:171], v[0:15]
	s_waitcnt lgkmcnt(0)
	v_mfma_f32_32x32x16_bf16 v[0:15], v[88:91], v[146:149], v[0:15]
	v_mfma_f32_32x32x16_bf16 v[0:15], v[84:87], v[182:185], v[0:15]
	v_mfma_f32_32x32x16_bf16 v[0:15], v[80:83], v[186:189], v[0:15]
	v_mfma_f32_32x32x16_bf16 v[16:31], v[92:95], v[190:193], v[16:31]
	s_waitcnt lgkmcnt(0)
	s_cmp_lg_u32 s40, 0
	s_cbranch_scc0 .Lmla_nobar6
	s_barrier
.Lmla_nobar6:
	v_mfma_f32_32x32x16_bf16 v[16:31], v[88:91], v[150:153], v[16:31]
	v_mfma_f32_32x32x16_bf16 v[16:31], v[84:87], v[208:211], v[16:31]
	v_mfma_f32_32x32x16_bf16 v[16:31], v[80:83], v[212:215], v[16:31]
	s_cmp_lt_i32 s47, s54
	s_cbranch_scc0 .Lmla_w2_tail
	s_waitcnt vmcnt(3)
	ds_write_b128 v200, v[136:139]
	ds_write_b128 v201, v[132:135] offset:26624
	s_cmp_lg_u32 s8, 0
	s_cbranch_scc0 .LBB0_991
	ds_write_b128 v239, v[140:143] offset:128
.LBB0_991:
	v_max3_f32 v81, v64, v65, v66
	v_max3_f32 v82, v67, v68, v69
	v_max3_f32 v83, v70, v71, v72
	v_max3_f32 v81, v81, v73, v74
	v_max3_f32 v82, v82, v75, v76
	v_max3_f32 v83, v83, v77, v78
	v_max3_f32 v81, v81, v79, v48
	v_max3_f32 v82, v82, v49, v50
	v_max3_f32 v83, v83, v51, v52
	v_max3_f32 v81, v81, v53, v54
	v_max3_f32 v82, v82, v55, v56
	v_max3_f32 v83, v83, v57, v58
	v_max3_f32 v81, v81, v59, v60
	v_max3_f32 v82, v82, v61, v62
	v_max3_f32 v81, v81, v82, v83
	v_max_f32_e32 v81, v81, v63
	v_cmp_ge_f32_e32 vcc, s94, v81
	s_cmp_eq_u64 vcc, exec
	s_cbranch_scc0 .LBB0_996
.LBB0_992:
	v_exp_f32_e32 v64, v64
	v_exp_f32_e32 v65, v65
	v_exp_f32_e32 v66, v66
	v_add_f32_e32 v236, v64, v236
	v_exp_f32_e32 v67, v67
	v_add_f32_e32 v237, v65, v237
	v_exp_f32_e32 v68, v68
	v_add_f32_e32 v236, v66, v236
	v_exp_f32_e32 v69, v69
	v_add_f32_e32 v237, v67, v237
	v_exp_f32_e32 v70, v70
	v_add_f32_e32 v236, v68, v236
	v_exp_f32_e32 v71, v71
	v_add_f32_e32 v237, v69, v237
	v_exp_f32_e32 v72, v72
	v_add_f32_e32 v236, v70, v236
	v_exp_f32_e32 v73, v73
	v_add_f32_e32 v237, v71, v237
	v_exp_f32_e32 v74, v74
	v_add_f32_e32 v236, v72, v236
	v_exp_f32_e32 v75, v75
	v_add_f32_e32 v237, v73, v237
	v_exp_f32_e32 v76, v76
	v_add_f32_e32 v236, v74, v236
	v_exp_f32_e32 v77, v77
	v_add_f32_e32 v237, v75, v237
	v_exp_f32_e32 v78, v78
	v_add_f32_e32 v236, v76, v236
	v_exp_f32_e32 v79, v79
	v_add_f32_e32 v237, v77, v237
	v_exp_f32_e32 v48, v48
	v_add_f32_e32 v236, v78, v236
	v_exp_f32_e32 v49, v49
	v_add_f32_e32 v237, v79, v237
	v_exp_f32_e32 v50, v50
	v_add_f32_e32 v236, v48, v236
	v_exp_f32_e32 v51, v51
	v_add_f32_e32 v237, v49, v237
	v_exp_f32_e32 v52, v52
	v_add_f32_e32 v236, v50, v236
	v_exp_f32_e32 v53, v53
	v_add_f32_e32 v237, v51, v237
	v_exp_f32_e32 v54, v54
	v_add_f32_e32 v236, v52, v236
	v_exp_f32_e32 v55, v55
	v_add_f32_e32 v237, v53, v237
	v_exp_f32_e32 v56, v56
	v_add_f32_e32 v236, v54, v236
	v_exp_f32_e32 v57, v57
	v_add_f32_e32 v237, v55, v237
	v_exp_f32_e32 v58, v58
	v_add_f32_e32 v236, v56, v236
	v_exp_f32_e32 v59, v59
	v_add_f32_e32 v237, v57, v237
	v_exp_f32_e32 v60, v60
	v_add_f32_e32 v236, v58, v236
	v_exp_f32_e32 v61, v61
	v_add_f32_e32 v237, v59, v237
	v_exp_f32_e32 v62, v62
	v_add_f32_e32 v236, v60, v236
	v_exp_f32_e32 v63, v63
	v_add_f32_e32 v237, v61, v237
	v_add_f32_e32 v236, v62, v236
	v_add_f32_e32 v237, v63, v237
	v_cmp_gt_f32_e32 vcc, 1.0, v235
	v_cvt_pk_bf16_f32 v55, v54, v55
	v_cvt_pk_bf16_f32 v54, v52, v53
	v_cvt_pk_bf16_f32 v52, v48, v49
	v_cvt_pk_bf16_f32 v53, v50, v51
	v_cvt_pk_bf16_f32 v48, v56, v57
	v_cvt_pk_bf16_f32 v49, v58, v59
	v_cvt_pk_bf16_f32 v50, v60, v61
	v_cvt_pk_bf16_f32 v51, v62, v63
	v_cvt_pk_bf16_f32 v60, v64, v65
	v_cvt_pk_bf16_f32 v61, v66, v67
	v_cvt_pk_bf16_f32 v62, v68, v69
	v_cvt_pk_bf16_f32 v63, v70, v71
	v_cvt_pk_bf16_f32 v56, v72, v73
	v_cvt_pk_bf16_f32 v57, v74, v75
	v_cvt_pk_bf16_f32 v58, v76, v77
	v_cvt_pk_bf16_f32 v59, v78, v79
	s_cbranch_vccz .LBB0_964
	s_and_saveexec_b64 s[12:13], s[10:11]
	s_cbranch_execz .LBB0_963
	ds_write_b32 v202, v235 offset:43136
	s_branch .LBB0_963

.LBB0_973:
	s_cmp_ge_i32 s47, s54
	s_cbranch_scc1 .LBB0_975
	s_waitcnt vmcnt(0)
	ds_write_b128 v197, v[128:131] offset:26624
	s_branch .LBB0_975

; __device__ __forceinline__ void mla_softmax_rel_kp(f32x16& p0, f32x16& p1, f32x16& negm, bool first, float& l_reg, float& alpha, bf16x8& pa0, bf16x8& pa1, bf16x8& pa2, bf16x8& pa3) {
;     ...
;     { auto rr = __builtin_amdgcn_permlane32_swap(__float_as_uint(pmax), __float_as_uint(pmax), false, false); pmax = fmaxf(__uint_as_float(rr[0]), __uint_as_float(rr[1])); }
;     alpha = 1.f;
;     if (__builtin_expect(first || !__all(pmax <= THR2), 0)) {
;         const float d = first ? pmax : fmaxf(pmax, 0.f);
;         if (!first) alpha = __builtin_amdgcn_exp2f(-d);
;         const float nm = negm[0] - d;
; #pragma unroll
;         for (int r = 0; r < 16; ++r) { negm[r] = nm; p0[r] -= d; p1[r] -= d; }
;     }
.LBB0_989:
	s_andn2_b64 vcc, exec, s[42:43]
	s_cbranch_vccnz .LBB0_991
	s_waitcnt vmcnt(0)
	ds_write_b128 v201, v[132:135] offset:26624
	s_branch .LBB0_991
.LBB0_995:
	v_mov_b32_e32 v49, v48
	s_nop 1
	v_permlane32_swap_b32_e32 v48, v49
	v_max_f32_e32 v48, v48, v49
	v_max_f32_e32 v33, v48, v48
	v_max_f32_e32 v34, 0, v33
	v_exp_f32_e64 v144, -v34
	v_sub_f32_e32 v48, v32, v34
	v_mul_f32_e32 v236, v236, v144
	v_mul_f32_e32 v237, v237, v144
	v_pk_add_f32 v[64:65], v[64:65], v[34:35] op_sel_hi:[1,0] neg_lo:[0,1] neg_hi:[0,1]
	v_pk_add_f32 v[80:81], v[80:81], v[34:35] op_sel_hi:[1,0] neg_lo:[0,1] neg_hi:[0,1]
	v_pk_add_f32 v[66:67], v[66:67], v[34:35] op_sel_hi:[1,0] neg_lo:[0,1] neg_hi:[0,1]
	v_pk_add_f32 v[82:83], v[82:83], v[34:35] op_sel_hi:[1,0] neg_lo:[0,1] neg_hi:[0,1]
	v_pk_add_f32 v[68:69], v[68:69], v[34:35] op_sel_hi:[1,0] neg_lo:[0,1] neg_hi:[0,1]
	v_pk_add_f32 v[84:85], v[84:85], v[34:35] op_sel_hi:[1,0] neg_lo:[0,1] neg_hi:[0,1]
	v_pk_add_f32 v[70:71], v[70:71], v[34:35] op_sel_hi:[1,0] neg_lo:[0,1] neg_hi:[0,1]
	v_pk_add_f32 v[86:87], v[86:87], v[34:35] op_sel_hi:[1,0] neg_lo:[0,1] neg_hi:[0,1]
	v_pk_add_f32 v[72:73], v[72:73], v[34:35] op_sel_hi:[1,0] neg_lo:[0,1] neg_hi:[0,1]
	v_pk_add_f32 v[88:89], v[88:89], v[34:35] op_sel_hi:[1,0] neg_lo:[0,1] neg_hi:[0,1]
	v_pk_add_f32 v[74:75], v[74:75], v[34:35] op_sel_hi:[1,0] neg_lo:[0,1] neg_hi:[0,1]
	v_pk_add_f32 v[90:91], v[90:91], v[34:35] op_sel_hi:[1,0] neg_lo:[0,1] neg_hi:[0,1]
	v_pk_add_f32 v[76:77], v[76:77], v[34:35] op_sel_hi:[1,0] neg_lo:[0,1] neg_hi:[0,1]
	v_pk_add_f32 v[92:93], v[92:93], v[34:35] op_sel_hi:[1,0] neg_lo:[0,1] neg_hi:[0,1]
	v_pk_add_f32 v[78:79], v[78:79], v[34:35] op_sel_hi:[1,0] neg_lo:[0,1] neg_hi:[0,1]
	v_pk_add_f32 v[94:95], v[94:95], v[34:35] op_sel_hi:[1,0] neg_lo:[0,1] neg_hi:[0,1]
	v_mov_b32_e32 v49, v48
	v_mov_b32_e32 v50, v48
	v_mov_b32_e32 v51, v48
	v_mov_b32_e32 v52, v48
	v_mov_b32_e32 v53, v48
	v_mov_b32_e32 v54, v48
	v_mov_b32_e32 v55, v48
	v_mov_b32_e32 v56, v48
	v_mov_b32_e32 v57, v48
	v_mov_b32_e32 v58, v48
	v_mov_b32_e32 v59, v48
	v_mov_b32_e32 v60, v48
	v_mov_b32_e32 v61, v48
	v_mov_b32_e32 v62, v48
	v_mov_b32_e32 v63, v48
	v_mov_b32_e32 v32, v48
	v_mov_b32_e32 v33, v48
	v_mov_b32_e32 v34, v48
	v_mov_b32_e32 v35, v48
	v_mov_b32_e32 v36, v48
	v_mov_b32_e32 v37, v48
	v_mov_b32_e32 v38, v48
	v_mov_b32_e32 v39, v48
	v_mov_b32_e32 v40, v48
	v_mov_b32_e32 v41, v48
	v_mov_b32_e32 v42, v48
	v_mov_b32_e32 v43, v48
	v_mov_b32_e32 v44, v48
	v_mov_b32_e32 v45, v48
	v_mov_b32_e32 v46, v48
	v_mov_b32_e32 v47, v48
	s_branch .LBB0_977
.LBB0_996:
	v_mov_b32_e32 v82, v81
	s_nop 1
	v_permlane32_swap_b32_e32 v81, v82
	v_max_f32_e32 v81, v81, v82
	v_max_f32_e32 v33, v81, v81
	v_max_f32_e32 v34, 0, v33
	v_exp_f32_e64 v235, -v34
	v_sub_f32_e32 v32, v32, v34
	v_mul_f32_e32 v236, v236, v235
	v_mul_f32_e32 v237, v237, v235
	v_pk_add_f32 v[64:65], v[64:65], v[34:35] op_sel_hi:[1,0] neg_lo:[0,1] neg_hi:[0,1]
	v_pk_add_f32 v[48:49], v[48:49], v[34:35] op_sel_hi:[1,0] neg_lo:[0,1] neg_hi:[0,1]
	v_pk_add_f32 v[66:67], v[66:67], v[34:35] op_sel_hi:[1,0] neg_lo:[0,1] neg_hi:[0,1]
	v_pk_add_f32 v[50:51], v[50:51], v[34:35] op_sel_hi:[1,0] neg_lo:[0,1] neg_hi:[0,1]
	v_pk_add_f32 v[68:69], v[68:69], v[34:35] op_sel_hi:[1,0] neg_lo:[0,1] neg_hi:[0,1]
	v_pk_add_f32 v[52:53], v[52:53], v[34:35] op_sel_hi:[1,0] neg_lo:[0,1] neg_hi:[0,1]
	v_pk_add_f32 v[70:71], v[70:71], v[34:35] op_sel_hi:[1,0] neg_lo:[0,1] neg_hi:[0,1]
	v_pk_add_f32 v[54:55], v[54:55], v[34:35] op_sel_hi:[1,0] neg_lo:[0,1] neg_hi:[0,1]
	v_pk_add_f32 v[72:73], v[72:73], v[34:35] op_sel_hi:[1,0] neg_lo:[0,1] neg_hi:[0,1]
	v_pk_add_f32 v[56:57], v[56:57], v[34:35] op_sel_hi:[1,0] neg_lo:[0,1] neg_hi:[0,1]
	v_pk_add_f32 v[74:75], v[74:75], v[34:35] op_sel_hi:[1,0] neg_lo:[0,1] neg_hi:[0,1]
	v_pk_add_f32 v[58:59], v[58:59], v[34:35] op_sel_hi:[1,0] neg_lo:[0,1] neg_hi:[0,1]
	v_pk_add_f32 v[76:77], v[76:77], v[34:35] op_sel_hi:[1,0] neg_lo:[0,1] neg_hi:[0,1]
	v_pk_add_f32 v[60:61], v[60:61], v[34:35] op_sel_hi:[1,0] neg_lo:[0,1] neg_hi:[0,1]
	v_pk_add_f32 v[78:79], v[78:79], v[34:35] op_sel_hi:[1,0] neg_lo:[0,1] neg_hi:[0,1]
	v_pk_add_f32 v[62:63], v[62:63], v[34:35] op_sel_hi:[1,0] neg_lo:[0,1] neg_hi:[0,1]
	v_mov_b32_e32 v33, v32
	v_mov_b32_e32 v34, v32
	v_mov_b32_e32 v35, v32
	v_mov_b32_e32 v36, v32
	v_mov_b32_e32 v37, v32
	v_mov_b32_e32 v38, v32
	v_mov_b32_e32 v39, v32
	v_mov_b32_e32 v40, v32
	v_mov_b32_e32 v41, v32
	v_mov_b32_e32 v42, v32
	v_mov_b32_e32 v43, v32
	v_mov_b32_e32 v44, v32
	v_mov_b32_e32 v45, v32
	v_mov_b32_e32 v46, v32
	v_mov_b32_e32 v47, v32
	s_branch .LBB0_992
; #define LDS_WAIT() asm volatile("s_waitcnt lgkmcnt(0)" ::: "memory")
; __device__ __forceinline__ int crow(int r, int hi) { return (r & 3) + 8 * (r >> 2) + 4 * hi; }
; #define HBAR() do { asm volatile("s_waitcnt lgkmcnt(0)" ::: "memory"); __builtin_amdgcn_s_barrier(); asm volatile("" ::: "memory"); } while (0)
; __device__ __forceinline__ void mla_unit2(const Params& P, unsigned char* lds, int h, int rb, int grp, bool dry = false) {
;     ...
;     if (dry) Gp = (bf16_t*)(ws + WS_END) + h * 64 - (size_t)(seq0 + t0) * ldg + (size_t)((rb & 7) * 256) * ldg;
;     bf16_t* Gw = Gp + (size_t)(seq0 + t0 + wid * 32) * ldg + r32;
;     bf16_t gq[32];
; #pragma unroll
;     for (int r = 0; r < 16; ++r) { const int orow = crow(r, hi); gq[2 * r] = Gw[(size_t)orow * ldg]; gq[2 * r + 1] = Gw[(size_t)orow * ldg + 32]; }
;     pv_both_kp(o[0], o[1], vb0 + A_VBUF, pa0, pa1, pa2, pa3);
;     HBAR();
;     if (!hoff) HBAR();
;     ...
;     if (hi == 0) li_l[r32] = l_reg; LDS_WAIT();
.LBB0_997:
	v_add_f32_e32 v203, v236, v237
	v_mov_b32_e32 v234, v203
	s_nop 1
	v_permlane32_swap_b32_e32 v203, v234
	v_add_f32_e32 v203, v203, v234
	s_add_u32 s4, s36, s53
	s_addc_u32 s5, s37, 0
	s_add_u32 s4, s4, s38
	s_addc_u32 s5, s5, s39
	s_mul_hi_i32 s8, s57, 0xc00
	s_mulk_i32 s57, 0xc00
	s_add_u32 s4, s4, s57
	s_addc_u32 s5, s5, s8
	v_lshlrev_b32_e32 v144, 1, v195
	v_mul_u32_u24_e32 v34, 0x1800, v194
	v_lshl_add_u64 v[32:33], s[4:5], 0, v[144:145]
	s_mov_b64 s[4:5], 0x2000340
	v_lshlrev_b32_e32 v144, 1, v34
	v_lshl_or_b32 v34, v194, 2, 1
	v_lshl_add_u64 v[32:33], v[32:33], 0, s[4:5]
	v_mul_u32_u24_e32 v35, 0x600, v34
	v_lshl_add_u64 v[36:37], v[32:33], 0, v[144:145]
	v_lshlrev_b32_e32 v144, 1, v35
	v_lshl_add_u64 v[38:39], v[32:33], 0, v[144:145]
	v_add_u32_e32 v40, 0x1800, v144
	v_mov_b32_e32 v41, v145
	v_lshl_add_u64 v[40:41], v[32:33], 0, v[40:41]
	global_load_ushort v45, v[36:37], off
	global_load_ushort v82, v[36:37], off offset:64
	global_load_ushort v81, v[38:39], off
	global_load_ushort v80, v[38:39], off offset:64
	global_load_ushort v79, v[38:39], off offset:3072
	global_load_ushort v78, v[38:39], off offset:3136
	global_load_ushort v77, v[40:41], off
	global_load_ushort v75, v[40:41], off offset:64
	v_add_u32_e32 v36, 0x5400, v144
	v_mov_b32_e32 v37, v145
	v_add_u32_e32 v38, 0x6000, v144
	v_mov_b32_e32 v39, v145
	v_add_u32_e32 v42, 0x7800, v144
	v_mov_b32_e32 v43, v145
	v_lshl_add_u64 v[36:37], v[32:33], 0, v[36:37]
	v_lshl_add_u64 v[38:39], v[32:33], 0, v[38:39]
	v_add_u32_e32 v40, 0x6c00, v144
	v_mov_b32_e32 v41, v145
	v_lshl_add_u64 v[42:43], v[32:33], 0, v[42:43]
	v_lshl_add_u64 v[40:41], v[32:33], 0, v[40:41]
	global_load_ushort v76, v[36:37], off
	global_load_ushort v74, v[36:37], off offset:64
	global_load_ushort v73, v[38:39], off
	global_load_ushort v72, v[38:39], off offset:64
	global_load_ushort v71, v[40:41], off
	global_load_ushort v70, v[40:41], off offset:64
	global_load_ushort v69, v[42:43], off
	global_load_ushort v67, v[42:43], off offset:64
	v_add_u32_e32 v36, 0xb400, v144
	v_mov_b32_e32 v37, v145
	v_add_u32_e32 v38, 0xc000, v144
	v_mov_b32_e32 v39, v145
	v_add_u32_e32 v42, 0xd800, v144
	v_mov_b32_e32 v43, v145
	v_lshl_add_u64 v[36:37], v[32:33], 0, v[36:37]
	v_lshl_add_u64 v[38:39], v[32:33], 0, v[38:39]
	v_add_u32_e32 v40, 0xcc00, v144
	v_mov_b32_e32 v41, v145
	v_lshl_add_u64 v[42:43], v[32:33], 0, v[42:43]
	v_lshl_add_u64 v[40:41], v[32:33], 0, v[40:41]
	global_load_ushort v68, v[36:37], off
	global_load_ushort v66, v[36:37], off offset:64
	global_load_ushort v65, v[38:39], off
	global_load_ushort v64, v[38:39], off offset:64
	global_load_ushort v47, v[40:41], off
	global_load_ushort v46, v[40:41], off offset:64
	global_load_ushort v44, v[42:43], off
	s_nop 0
	global_load_ushort v42, v[42:43], off offset:64
	v_add_u32_e32 v36, 0x11400, v144
	v_mov_b32_e32 v37, v145
	v_add_u32_e32 v38, 0x12000, v144
	v_mov_b32_e32 v39, v145
	v_lshl_add_u64 v[36:37], v[32:33], 0, v[36:37]
	v_lshl_add_u64 v[38:39], v[32:33], 0, v[38:39]
	v_add_u32_e32 v40, 0x12c00, v144
	v_mov_b32_e32 v41, v145
	v_add_u32_e32 v144, 0x13800, v144
	v_lshl_add_u64 v[84:85], v[32:33], 0, v[40:41]
	v_lshl_add_u64 v[86:87], v[32:33], 0, v[144:145]
	global_load_ushort v43, v[36:37], off
	global_load_ushort v41, v[36:37], off offset:64
	global_load_ushort v40, v[38:39], off
	s_nop 0
	global_load_ushort v39, v[38:39], off offset:64
	s_nop 0
	global_load_ushort v38, v[84:85], off
	global_load_ushort v37, v[84:85], off offset:64
	global_load_ushort v36, v[86:87], off
	global_load_ushort v35, v[86:87], off offset:64
	ds_read_b64_tr_b16 v[84:85], v204 offset:0
	ds_read_b64_tr_b16 v[86:87], v204 offset:0x100
	ds_read_b64_tr_b16 v[88:89], v204 offset:0x800
	ds_read_b64_tr_b16 v[90:91], v204 offset:0x900
	ds_read_b64_tr_b16 v[92:93], v204 offset:0x1000
	ds_read_b64_tr_b16 v[94:95], v204 offset:0x1100
	ds_read_b64_tr_b16 v[96:97], v204 offset:0x1800
	ds_read_b64_tr_b16 v[98:99], v204 offset:0x1900
	ds_read_b64_tr_b16 v[100:101], v204 offset:0x200
	ds_read_b64_tr_b16 v[102:103], v204 offset:0x300
	ds_read_b64_tr_b16 v[104:105], v204 offset:0xa00
	ds_read_b64_tr_b16 v[106:107], v204 offset:0xb00
	ds_read_b64_tr_b16 v[108:109], v204 offset:0x1200
	ds_read_b64_tr_b16 v[110:111], v204 offset:0x1300
	ds_read_b64_tr_b16 v[112:113], v204 offset:0x1a00
	ds_read_b64_tr_b16 v[114:115], v204 offset:0x1b00
	s_waitcnt lgkmcnt(8)
	s_nop 0
	v_mfma_f32_32x32x16_bf16 v[0:15], v[60:63], v[84:87], v[0:15]
	s_waitcnt lgkmcnt(0)
	v_mfma_f32_32x32x16_bf16 v[0:15], v[56:59], v[88:91], v[0:15]
	v_mfma_f32_32x32x16_bf16 v[0:15], v[52:55], v[92:95], v[0:15]
	v_mfma_f32_32x32x16_bf16 v[0:15], v[48:51], v[96:99], v[0:15]
	v_mfma_f32_32x32x16_bf16 v[16:31], v[60:63], v[100:103], v[16:31]
	s_waitcnt lgkmcnt(0)
	s_cmp_lg_u32 s40, 0
	s_cbranch_scc0 .Lmla_nobar8
	s_barrier
.Lmla_nobar8:
	s_andn2_b64 vcc, exec, s[16:17]
	v_mfma_f32_32x32x16_bf16 v[16:31], v[56:59], v[104:107], v[16:31]
	v_mfma_f32_32x32x16_bf16 v[16:31], v[52:55], v[108:111], v[16:31]
	v_mfma_f32_32x32x16_bf16 v[16:31], v[48:51], v[112:115], v[16:31]
	s_cbranch_vccnz .LBB0_999
	s_waitcnt lgkmcnt(0)
	s_barrier
